# rowpass0: input / ctx base pointers loaded once before the row loop (no dependent pointer load + full wait per row)
# speedup vs baseline: 1.0066x; 1.0033x over previous
.LBB0_132:
	s_or_b64 exec, exec, s[0:1]
	v_readlane_b32 s0, v255, 2
	v_readlane_b32 s1, v255, 3
	s_waitcnt lgkmcnt(0)
	v_mov_b32_e32 v0, v190
	v_mov_b32_e32 v1, v190
	s_barrier
	s_mov_b32 s2, s94
	v_ashrrev_i32_e32 v1, 6, v1
	s_nop 0
	v_lshl_add_u32 v16, s2, 3, v1
	s_movk_i32 s2, 0x4200
	v_cmp_gt_i32_e32 vcc, s2, v16
	s_and_saveexec_b64 s[6:7], vcc
	s_cbranch_execz .LBB0_145
	s_load_dwordx2 s[2:3], s[0:1], 0xf0
	s_load_dwordx2 s[38:39], s[0:1], 0x0
	s_load_dwordx2 s[40:41], s[0:1], 0x10
	v_and_b32_e32 v1, 63, v0
	v_mov_b32_e32 v19, 0
	v_lshlrev_b32_e32 v0, 2, v1
	v_lshlrev_b32_e32 v18, 3, v1
	s_waitcnt lgkmcnt(0)
	s_add_u32 s8, s2, 0x3180000
	s_addc_u32 s9, s3, 0
	s_add_u32 s10, s2, 0x31aa000
	s_addc_u32 s11, s3, 0
	s_add_u32 s12, s0, 16
	s_addc_u32 s13, s1, 0
	s_add_u32 s14, s2, 0xf37e000
	s_addc_u32 s15, s3, 0
	v_or_b32_e32 v2, 0x100, v0
	v_or_b32_e32 v4, 0x200, v0
	v_or_b32_e32 v6, 0x300, v0
	v_lshl_add_u64 v[8:9], s[2:3], 0, v[18:19]
	s_mov_b64 s[2:3], 0x33aa000
	v_cmp_eq_u32_e32 vcc, 0, v1
	s_movk_i32 s24, 0x100
	s_lshl_b32 s25, s36, 3
	v_lshl_add_u64 v[20:21], v[8:9], 0, s[2:3]
	s_mov_b64 s[16:17], 0
	s_mov_b32 s26, 0x3e0f83e1
	s_movk_i32 s27, 0xdf00
	s_movk_i32 s28, 0xff
	s_movk_i32 s29, 0xff00
	v_lshlrev_b32_e32 v18, 2, v0
	s_mov_b64 s[18:19], 0x1000
	s_movk_i32 s30, 0x880
	v_lshlrev_b32_e32 v22, 2, v2
	v_lshlrev_b32_e32 v24, 2, v4
	v_lshlrev_b32_e32 v26, 2, v6
	s_movk_i32 s31, 0x41ff
	v_mov_b32_e32 v31, 0x3000
	s_branch .LBB0_135

.LBB0_135:
	v_mul_hi_i32 v0, v16, s26
	v_lshrrev_b32_e32 v1, 31, v0
	v_ashrrev_i32_e32 v0, 11, v0
	v_add_u32_e32 v23, v0, v1
	v_mul_i32_i24_e32 v0, 0xffffdf00, v23
	v_mad_i32_i24 v2, v23, s27, v16
	v_lshl_add_u32 v1, v23, 13, v0
	v_cmp_gt_i32_e64 s[2:3], s24, v2
	v_cmp_lt_i32_e64 s[4:5], s28, v2
	v_add3_u32 v0, v16, v1, s29
	s_and_saveexec_b64 s[20:21], s[4:5]
	s_xor_b64 s[20:21], exec, s[20:21]
	s_load_dwordx2 s[22:23], s[0:1], 0xe8
	v_add3_u32 v28, v16, v1, s29
	s_or_saveexec_b64 s[20:21], s[20:21]
	s_waitcnt lgkmcnt(0)
	v_mov_b64_e32 v[32:33], s[22:23]
	v_lshl_add_u32 v1, v23, 8, v2
	s_xor_b64 exec, exec, s[20:21]
	v_lshl_add_u32 v28, v23, 8, v2
	v_mov_b64_e32 v[32:33], s[10:11]
	s_or_b64 exec, exec, s[20:21]
	s_and_saveexec_b64 s[20:21], s[4:5]
	s_xor_b64 s[4:5], exec, s[20:21]
	s_or_saveexec_b64 s[4:5], s[4:5]
	v_mov_b32_e32 v30, 1.0
	v_mov_b64_e32 v[2:3], s[38:39]
	s_xor_b64 exec, exec, s[4:5]
	v_mov_b32_e32 v30, 0x3fb504f3
	v_mov_b64_e32 v[2:3], s[40:41]
	v_mov_b32_e32 v0, v1
	s_or_b64 exec, exec, s[4:5]
	v_ashrrev_i32_e32 v1, 31, v0
	v_lshlrev_b64 v[0:1], 12, v[0:1]
	v_ashrrev_i32_e32 v29, 31, v28
	v_lshlrev_b64 v[28:29], 12, v[28:29]
	v_lshl_add_u64 v[28:29], v[32:33], 0, v[28:29]
	v_lshl_add_u64 v[28:29], v[28:29], 0, v[18:19]
	v_ashrrev_i32_e32 v17, 31, v16
	v_lshl_add_u64 v[0:1], v[2:3], 0, v[0:1]
	v_lshl_add_u64 v[34:35], v[0:1], 0, v[18:19]
	global_load_dwordx4 v[12:15], v[34:35], off
	global_load_dwordx4 v[8:11], v[34:35], off offset:1024
	global_load_dwordx4 v[4:7], v[34:35], off offset:2048
	global_load_dwordx4 v[0:3], v[34:35], off offset:3072
	s_waitcnt vmcnt(3)
	v_pk_mul_f32 v[34:35], v[30:31], v[14:15] op_sel_hi:[0,1]
	v_pk_mul_f32 v[32:33], v[30:31], v[12:13] op_sel_hi:[0,1]
	s_waitcnt vmcnt(2)
	v_pk_mul_f32 v[38:39], v[30:31], v[10:11] op_sel_hi:[0,1]
	v_pk_mul_f32 v[36:37], v[30:31], v[8:9] op_sel_hi:[0,1]
	s_waitcnt vmcnt(1)
	v_pk_mul_f32 v[42:43], v[30:31], v[6:7] op_sel_hi:[0,1]
	v_pk_mul_f32 v[40:41], v[30:31], v[4:5] op_sel_hi:[0,1]
	s_waitcnt vmcnt(0)
	v_pk_mul_f32 v[46:47], v[30:31], v[2:3] op_sel_hi:[0,1]
	v_pk_mul_f32 v[44:45], v[30:31], v[0:1] op_sel_hi:[0,1]
	s_cmp_eq_u64 s[2:3], 0
	s_cbranch_scc1 .Lrp0_nocopy
	global_store_dwordx4 v[28:29], v[32:35], off
	global_store_dwordx4 v[28:29], v[36:39], off offset:1024
	global_store_dwordx4 v[28:29], v[40:43], off offset:2048
	global_store_dwordx4 v[28:29], v[44:47], off offset:3072
